# v27 plus software-pipelined gather_h loop: next iteration's P1/EIDX/G loads prefetched under the current iteration's erf math
# speedup vs baseline: 1.0105x; 1.0105x over previous
; DI float bflo(u32 w) { return __uint_as_float(w << 16); }
; DI float bfhi(u32 w) { return __uint_as_float(w & 0xffff0000u); }
; DI void phase_gather_h(int layer) {
;     ...
; #pragma unroll
;     for (int k = 0; k < 4; ++k) { su[k] = SU[e[k]]; sv[k] = SV[e[k]]; }
;     float sd[4] = {0.f, 0.f, 0.f, 0.f};
; #pragma unroll
;     for (int c = 0; c < 8; ++c) { sd[0] += bflo(pr[c].x); sd[1] += bfhi(pr[c].x); sd[2] += bflo(pr[c].y); sd[3] += bfhi(pr[c].y); }
;     const float gq[4] = {gv.x, gv.y, gv.z, gv.w};
;     float hvv[4];
; #pragma unroll
;     for (int k = 0; k < 4; ++k) {
;       const float z = sd[k] * su[k];
;       hvv[k] = 0.5f * z * (1.f + erff(z * 0.70710678118654752f)) * gq[k] * sv[k];
;     }
;     uint2 o; o.x = pack2(hvv[0], hvv[1]); o.y = pack2(hvv[2], hvv[3]);
;     *(uint2*)(HP + i) = o;
.LBB0_1698:
	s_or_b64 exec, exec, s[56:57]
	s_brev_b32 s0, -2
	v_bfi_b32 v10, s0, v12, v10
	v_bfi_b32 v14, s0, v18, v14
	v_mul_f32_e32 v8, 0.5, v8
	v_add_f32_e32 v10, 1.0, v10
	v_mul_f32_e32 v15, 0.5, v16
	v_add_f32_e32 v14, 1.0, v14
	v_mul_f32_e32 v8, v8, v10
	v_mul_f32_e32 v14, v15, v14
	v_bfi_b32 v15, s0, v30, v29
	v_mul_f32_e32 v3, v3, v8
	v_bfi_b32 v8, s0, v13, v9
	v_mul_f32_e32 v4, v4, v14
	v_mul_f32_e32 v11, 0.5, v11
	v_mul_f32_e32 v14, 0.5, v28
	v_add_f32_e32 v15, 1.0, v15
	v_add_f32_e32 v8, 1.0, v8
	v_mul_f32_e32 v14, v14, v15
	v_mul_f32_e32 v8, v11, v8
	v_readlane_b32 s0, v254, 18
	v_mul_f32_e32 v2, v2, v14
	v_mul_f32_e32 v5, v5, v8
	v_add_u32_e32 v24, s0, v24
	s_mov_b32 s56, 0x27ffff
	v_mul_f32_e32 v4, v27, v4
	v_mul_f32_e32 v2, v26, v2
	v_mul_f32_e32 v3, v25, v3
	s_waitcnt vmcnt(10)
	v_mul_f32_e32 v0, v0, v5
	v_cmp_lt_i32_e32 vcc, s56, v24
	v_readlane_b32 s0, v254, 53
	v_cvt_pk_bf16_f32 v2, v2, v3
	v_cvt_pk_bf16_f32 v3, v4, v0
	v_lshl_add_u64 v[4:5], v[6:7], 1, s[52:53]
	s_or_b64 s[54:55], vcc, s[54:55]
	v_add_u32_e32 v6, s0, v6
	global_store_dwordx2 v[4:5], v[2:3], off
	s_andn2_b64 exec, exec, s[54:55]
	s_cbranch_execz .LBB0_1715
	s_waitcnt vmcnt(1)
	v_mov_b64_e32 v[26:27], v[40:41]
	v_mov_b64_e32 v[2:3], v[42:43]
	v_mov_b64_e32 v[4:5], v[44:45]
	v_mov_b64_e32 v[22:23], v[46:47]
	v_mov_b64_e32 v[20:21], v[48:49]
	v_mov_b64_e32 v[18:19], v[50:51]
	v_mov_b64_e32 v[16:17], v[52:53]
	v_mov_b64_e32 v[14:15], v[54:55]
	v_mov_b64_e32 v[12:13], v[56:57]
	v_mov_b64_e32 v[10:11], v[58:59]
	v_mov_b64_e32 v[8:9], v[60:61]
	s_branch .Lmy_gh_body

; DI float bflo(u32 w) { return __uint_as_float(w << 16); }
; DI float bfhi(u32 w) { return __uint_as_float(w & 0xffff0000u); }
; DI void phase_gather_h(int layer) {
;     ...
;   for (int i4 = blockIdx.x * NTH + tid; i4 < NT * 32; i4 += gridDim.x * NTH) {
;     const int i = i4 * 4, t = i >> 7, pos = i & 127;
;     uint2 pr[8];
; #pragma unroll
;     for (int c = 0; c < 8; ++c) pr[c] = *(const uint2*)(P1 + ((size_t)t * 8 + c) * 128 + pos);
;     const uint2 ev = *(const uint2*)(EIDX + i);
;     const float4 gv = *(const float4*)(G + i);
;     const int e[4] = {(int)(ev.x & 0xffffu), (int)(ev.x >> 16), (int)(ev.y & 0xffffu), (int)(ev.y >> 16)};
;     float su[4], sv[4];
; #pragma unroll
;     for (int k = 0; k < 4; ++k) { su[k] = SU[e[k]]; sv[k] = SV[e[k]]; }
;     float sd[4] = {0.f, 0.f, 0.f, 0.f};
; #pragma unroll
;     for (int c = 0; c < 8; ++c) { sd[0] += bflo(pr[c].x); sd[1] += bfhi(pr[c].x); sd[2] += bflo(pr[c].y); sd[3] += bfhi(pr[c].y); }
;     const float gq[4] = {gv.x, gv.y, gv.z, gv.w};
;     float hvv[4];
; #pragma unroll
;     for (int k = 0; k < 4; ++k) {
;       const float z = sd[k] * su[k];
;       hvv[k] = 0.5f * z * (1.f + erff(z * 0.70710678118654752f)) * gq[k] * sv[k];
.Lmy_gh_body:
	v_ashrrev_i32_e32 v7, 31, v6
	v_lshlrev_b32_sdwa v0, v232, v26 dst_sel:DWORD dst_unused:UNUSED_PAD src0_sel:DWORD src1_sel:WORD_0
	v_lshlrev_b32_sdwa v25, v232, v26 dst_sel:DWORD dst_unused:UNUSED_PAD src0_sel:DWORD src1_sel:WORD_1
	v_lshlrev_b32_sdwa v28, v232, v27 dst_sel:DWORD dst_unused:UNUSED_PAD src0_sel:DWORD src1_sel:WORD_0
	v_lshlrev_b32_sdwa v29, v232, v27 dst_sel:DWORD dst_unused:UNUSED_PAD src0_sel:DWORD src1_sel:WORD_1
	global_load_dword v30, v0, s[46:47]
	global_load_dword v26, v0, s[48:49]
	global_load_dword v33, v25, s[46:47]
	s_nop 0
	global_load_dword v25, v25, s[48:49]
	s_nop 0
	global_load_dword v32, v28, s[46:47]
	global_load_dword v27, v28, s[48:49]
	global_load_dword v31, v29, s[46:47]
	global_load_dword v0, v29, s[48:49]
	v_readlane_b32 s56, v254, 53
	s_nop 1
	v_add_u32_e32 v62, s56, v6
	v_ashrrev_i32_e32 v63, 31, v62
	v_lshl_add_u64 v[64:65], v[62:63], 1, s[42:43]
	global_load_dwordx2 v[40:41], v[64:65], off
	v_readlane_b32 s56, v254, 18
	s_nop 1
	v_add_u32_e32 v66, s56, v24
	v_ashrrev_i32_e32 v66, 5, v66
	v_ashrrev_i32_e32 v67, 31, v66
	v_and_b32_e32 v68, 0x7c, v62
	v_lshlrev_b64 v[66:67], 11, v[66:67]
	v_lshlrev_b32_e32 v68, 1, v68
	v_mov_b32_e32 v69, 0
	v_lshl_add_u64 v[66:67], s[50:51], 0, v[66:67]
	v_lshl_add_u64 v[64:65], v[62:63], 2, s[44:45]
	v_lshl_add_u64 v[66:67], v[66:67], 0, v[68:69]
	global_load_dwordx4 v[42:45], v[64:65], off
	global_load_dwordx2 v[46:47], v[66:67], off
	global_load_dwordx2 v[48:49], v[66:67], off offset:256
	global_load_dwordx2 v[50:51], v[66:67], off offset:512
	global_load_dwordx2 v[52:53], v[66:67], off offset:768
	global_load_dwordx2 v[54:55], v[66:67], off offset:1024
	global_load_dwordx2 v[56:57], v[66:67], off offset:1280
	global_load_dwordx2 v[58:59], v[66:67], off offset:1536
	global_load_dwordx2 v[60:61], v[66:67], off offset:1792
	s_waitcnt vmcnt(25)
	v_lshlrev_b32_e32 v28, 16, v22
	v_add_f32_e32 v28, 0, v28
	s_waitcnt vmcnt(24)
	v_lshlrev_b32_e32 v29, 16, v20
	v_add_f32_e32 v28, v28, v29
	s_waitcnt vmcnt(23)
	v_lshlrev_b32_e32 v29, 16, v18
	v_add_f32_e32 v28, v28, v29
	s_waitcnt vmcnt(22)
	v_lshlrev_b32_e32 v29, 16, v16
	v_add_f32_e32 v28, v28, v29
	s_waitcnt vmcnt(21)
	v_lshlrev_b32_e32 v29, 16, v14
	v_add_f32_e32 v28, v28, v29
	s_waitcnt vmcnt(20)
	v_lshlrev_b32_e32 v29, 16, v12
	v_add_f32_e32 v28, v28, v29
	s_waitcnt vmcnt(19)
	v_lshlrev_b32_e32 v29, 16, v10
	v_add_f32_e32 v28, v28, v29
	s_waitcnt vmcnt(18)
	v_lshlrev_b32_e32 v29, 16, v8
	v_add_f32_e32 v28, v28, v29
	s_waitcnt vmcnt(17)
	v_mul_f32_e32 v28, v28, v30
	v_mul_f32_e32 v29, 0x3f3504f3, v28
	v_cmp_nlt_f32_e64 s[56:57], |v29|, 1.0
	s_and_saveexec_b64 s[58:59], s[56:57]
	s_xor_b64 s[56:57], exec, s[58:59]
	s_cbranch_execz .LBB0_1701
	s_mov_b32 s0, 0x378e98ab
	v_fma_f32 v30, |v29|, s0, v233
	s_mov_b32 s0, 0x3b7cd369
	v_fma_f32 v30, |v29|, v30, s0
	s_mov_b32 s0, 0xbcc618b2
	v_fma_f32 v30, |v29|, v30, s0
	s_mov_b32 s0, 0x3dda74e4
	v_fma_f32 v30, |v29|, v30, s0
	s_mov_b32 s0, 0x3f228afd
	v_fma_f32 v30, |v29|, v30, s0
	s_mov_b32 s0, 0x3e03c728
	v_fma_f32 v30, |v29|, v30, s0
	v_fma_f32 v30, |v29|, v30, |v29|
	v_mul_f32_e32 v34, 0xbfb8aa3b, v30
	s_mov_b32 s0, 0xbfb8aa3b
	v_fma_f32 v35, v30, s0, -v34
	v_rndne_f32_e32 v36, v34
	v_fmac_f32_e32 v35, 0xb2a5705f, v30
	v_sub_f32_e32 v34, v34, v36
	v_add_f32_e32 v34, v34, v35
	v_cvt_i32_f32_e32 v35, v36
	v_exp_f32_e32 v34, v34
	s_mov_b32 s0, 0x42ce8ed0
	v_cmp_nlt_f32_e32 vcc, s0, v30
	s_mov_b32 s0, 0xc2b17218
	v_ldexp_f32 v34, v34, v35
	v_cndmask_b32_e32 v34, 0, v34, vcc
	v_cmp_ngt_f32_e32 vcc, s0, v30
	s_nop 1
	v_cndmask_b32_e32 v30, v230, v34, vcc
	v_sub_f32_e32 v30, 1.0, v30
.LBB0_1701:
	s_andn2_saveexec_b64 s[56:57], s[56:57]
	v_mul_f32_e32 v30, v29, v29
	v_fmamk_f32 v34, v30, 0xba1345e1, v211
	v_fmaak_f32 v34, v30, v34, 0xbcdac9b8
	v_fmaak_f32 v34, v30, v34, 0x3de703be
	v_fmaak_f32 v34, v30, v34, 0xbec09330
	v_fmaak_f32 v30, v30, v34, 0x3e0375d0
	v_fma_f32 v30, |v29|, v30, |v29|
	s_or_b64 exec, exec, s[56:57]
	v_and_b32_e32 v22, 0xffff0000, v22
	v_add_f32_e32 v22, 0, v22
	v_and_b32_e32 v20, 0xffff0000, v20
	v_add_f32_e32 v20, v22, v20
	v_and_b32_e32 v18, 0xffff0000, v18
	v_add_f32_e32 v18, v20, v18
	v_and_b32_e32 v16, 0xffff0000, v16
	v_add_f32_e32 v16, v18, v16
	v_and_b32_e32 v14, 0xffff0000, v14
	v_add_f32_e32 v14, v16, v14
	v_and_b32_e32 v12, 0xffff0000, v12
	v_add_f32_e32 v12, v14, v12
	v_and_b32_e32 v10, 0xffff0000, v10
	v_add_f32_e32 v10, v12, v10
	v_and_b32_e32 v8, 0xffff0000, v8
	v_add_f32_e32 v8, v10, v8
	s_waitcnt vmcnt(15)
	v_mul_f32_e32 v8, v8, v33
	v_mul_f32_e32 v10, 0x3f3504f3, v8
	v_cmp_nlt_f32_e64 s[56:57], |v10|, 1.0
	s_and_saveexec_b64 s[58:59], s[56:57]
	s_xor_b64 s[56:57], exec, s[58:59]
	s_cbranch_execz .LBB0_1705
	s_mov_b32 s0, 0x378e98ab
	v_fma_f32 v12, |v10|, s0, v233
	s_mov_b32 s0, 0x3b7cd369
	v_fma_f32 v12, |v10|, v12, s0
	s_mov_b32 s0, 0xbcc618b2
	v_fma_f32 v12, |v10|, v12, s0
	s_mov_b32 s0, 0x3dda74e4
	v_fma_f32 v12, |v10|, v12, s0
	s_mov_b32 s0, 0x3f228afd
	v_fma_f32 v12, |v10|, v12, s0
	s_mov_b32 s0, 0x3e03c728
	v_fma_f32 v12, |v10|, v12, s0
	v_fma_f32 v12, |v10|, v12, |v10|
	v_mul_f32_e32 v14, 0xbfb8aa3b, v12
	s_mov_b32 s0, 0xbfb8aa3b
	v_fma_f32 v16, v12, s0, -v14
	v_rndne_f32_e32 v18, v14
	v_fmac_f32_e32 v16, 0xb2a5705f, v12
	v_sub_f32_e32 v14, v14, v18
	v_add_f32_e32 v14, v14, v16
	v_cvt_i32_f32_e32 v16, v18
	v_exp_f32_e32 v14, v14
	s_mov_b32 s0, 0x42ce8ed0
	v_cmp_nlt_f32_e32 vcc, s0, v12
	s_mov_b32 s0, 0xc2b17218
	v_ldexp_f32 v14, v14, v16
	v_cndmask_b32_e32 v14, 0, v14, vcc
	v_cmp_ngt_f32_e32 vcc, s0, v12
	s_nop 1
	v_cndmask_b32_e32 v12, v230, v14, vcc
	v_sub_f32_e32 v12, 1.0, v12
; DI float bflo(u32 w) { return __uint_as_float(w << 16); }
; DI float bfhi(u32 w) { return __uint_as_float(w & 0xffff0000u); }
; DI void phase_gather_h(int layer) {
;     ...
; #pragma unroll
;     for (int c = 0; c < 8; ++c) { sd[0] += bflo(pr[c].x); sd[1] += bfhi(pr[c].x); sd[2] += bflo(pr[c].y); sd[3] += bfhi(pr[c].y); }
;     const float gq[4] = {gv.x, gv.y, gv.z, gv.w};
;     float hvv[4];
; #pragma unroll
;     for (int k = 0; k < 4; ++k) {
;       const float z = sd[k] * su[k];
;       hvv[k] = 0.5f * z * (1.f + erff(z * 0.70710678118654752f)) * gq[k] * sv[k];
.LBB0_1705:
	s_andn2_saveexec_b64 s[56:57], s[56:57]
	v_mul_f32_e32 v12, v10, v10
	v_fmamk_f32 v14, v12, 0xba1345e1, v211
	v_fmaak_f32 v14, v12, v14, 0xbcdac9b8
	v_fmaak_f32 v14, v12, v14, 0x3de703be
	v_fmaak_f32 v14, v12, v14, 0xbec09330
	v_fmaak_f32 v12, v12, v14, 0x3e0375d0
	v_fma_f32 v12, |v10|, v12, |v10|
	s_or_b64 exec, exec, s[56:57]
	v_lshlrev_b32_e32 v14, 16, v23
	v_add_f32_e32 v14, 0, v14
	v_lshlrev_b32_e32 v16, 16, v21
	v_add_f32_e32 v14, v14, v16
	v_lshlrev_b32_e32 v16, 16, v19
	v_add_f32_e32 v14, v14, v16
	v_lshlrev_b32_e32 v16, 16, v17
	v_add_f32_e32 v14, v14, v16
	v_lshlrev_b32_e32 v16, 16, v15
	v_add_f32_e32 v14, v14, v16
	v_lshlrev_b32_e32 v16, 16, v13
	v_add_f32_e32 v14, v14, v16
	v_lshlrev_b32_e32 v16, 16, v11
	v_add_f32_e32 v14, v14, v16
	v_lshlrev_b32_e32 v16, 16, v9
	v_add_f32_e32 v14, v14, v16
	s_waitcnt vmcnt(13)
	v_mul_f32_e32 v16, v14, v32
	v_mul_f32_e32 v14, 0x3f3504f3, v16
	v_cmp_nlt_f32_e64 s[56:57], |v14|, 1.0
	s_and_saveexec_b64 s[58:59], s[56:57]
	s_xor_b64 s[56:57], exec, s[58:59]
	s_cbranch_execz .LBB0_1709
	s_mov_b32 s0, 0x378e98ab
	v_fma_f32 v18, |v14|, s0, v233
	s_mov_b32 s0, 0x3b7cd369
	v_fma_f32 v18, |v14|, v18, s0
	s_mov_b32 s0, 0xbcc618b2
	v_fma_f32 v18, |v14|, v18, s0
	s_mov_b32 s0, 0x3dda74e4
	v_fma_f32 v18, |v14|, v18, s0
	s_mov_b32 s0, 0x3f228afd
	v_fma_f32 v18, |v14|, v18, s0
	s_mov_b32 s0, 0x3e03c728
	v_fma_f32 v18, |v14|, v18, s0
	v_fma_f32 v18, |v14|, v18, |v14|
	v_mul_f32_e32 v20, 0xbfb8aa3b, v18
	s_mov_b32 s0, 0xbfb8aa3b
	v_fma_f32 v22, v18, s0, -v20
	v_rndne_f32_e32 v32, v20
	v_fmac_f32_e32 v22, 0xb2a5705f, v18
	v_sub_f32_e32 v20, v20, v32
	v_add_f32_e32 v20, v20, v22
	v_cvt_i32_f32_e32 v22, v32
	v_exp_f32_e32 v20, v20
	s_mov_b32 s0, 0x42ce8ed0
	v_cmp_nlt_f32_e32 vcc, s0, v18
	s_mov_b32 s0, 0xc2b17218
	v_ldexp_f32 v20, v20, v22
	v_cndmask_b32_e32 v20, 0, v20, vcc
	v_cmp_ngt_f32_e32 vcc, s0, v18
	s_nop 1
	v_cndmask_b32_e32 v18, v230, v20, vcc
	v_sub_f32_e32 v18, 1.0, v18
.LBB0_1709:
	s_andn2_saveexec_b64 s[56:57], s[56:57]
	v_mul_f32_e32 v18, v14, v14
	v_fmamk_f32 v20, v18, 0xba1345e1, v211
	v_fmaak_f32 v20, v18, v20, 0xbcdac9b8
	v_fmaak_f32 v20, v18, v20, 0x3de703be
	v_fmaak_f32 v20, v18, v20, 0xbec09330
	v_fmaak_f32 v18, v18, v20, 0x3e0375d0
	v_fma_f32 v18, |v14|, v18, |v14|
	s_or_b64 exec, exec, s[56:57]
	v_and_b32_e32 v20, 0xffff0000, v23
	v_add_f32_e32 v20, 0, v20
	v_and_b32_e32 v21, 0xffff0000, v21
	v_add_f32_e32 v20, v20, v21
	v_and_b32_e32 v19, 0xffff0000, v19
	v_add_f32_e32 v19, v20, v19
	v_and_b32_e32 v17, 0xffff0000, v17
	v_add_f32_e32 v17, v19, v17
	v_and_b32_e32 v15, 0xffff0000, v15
	v_add_f32_e32 v15, v17, v15
	v_and_b32_e32 v13, 0xffff0000, v13
	v_add_f32_e32 v13, v15, v13
	v_and_b32_e32 v11, 0xffff0000, v11
	v_add_f32_e32 v11, v13, v11
	v_and_b32_e32 v9, 0xffff0000, v9
	v_add_f32_e32 v9, v11, v9
	s_waitcnt vmcnt(11)
	v_mul_f32_e32 v11, v9, v31
	v_mul_f32_e32 v9, 0x3f3504f3, v11
	v_cmp_nlt_f32_e64 s[56:57], |v9|, 1.0
	s_and_saveexec_b64 s[58:59], s[56:57]
	s_xor_b64 s[56:57], exec, s[58:59]
	s_cbranch_execz .LBB0_1713
	s_mov_b32 s0, 0x378e98ab
	v_fma_f32 v13, |v9|, s0, v233
	s_mov_b32 s0, 0x3b7cd369
	v_fma_f32 v13, |v9|, v13, s0
	s_mov_b32 s0, 0xbcc618b2
	v_fma_f32 v13, |v9|, v13, s0
	s_mov_b32 s0, 0x3dda74e4
	v_fma_f32 v13, |v9|, v13, s0
	s_mov_b32 s0, 0x3f228afd
	v_fma_f32 v13, |v9|, v13, s0
	s_mov_b32 s0, 0x3e03c728
	v_fma_f32 v13, |v9|, v13, s0
	v_fma_f32 v13, |v9|, v13, |v9|
	v_mul_f32_e32 v15, 0xbfb8aa3b, v13
	s_mov_b32 s0, 0xbfb8aa3b
	v_fma_f32 v17, v13, s0, -v15
	v_rndne_f32_e32 v19, v15
	v_fmac_f32_e32 v17, 0xb2a5705f, v13
	v_sub_f32_e32 v15, v15, v19
	v_add_f32_e32 v15, v15, v17
	v_cvt_i32_f32_e32 v17, v19
	v_exp_f32_e32 v15, v15
	s_mov_b32 s0, 0x42ce8ed0
	v_cmp_nlt_f32_e32 vcc, s0, v13
	s_mov_b32 s0, 0xc2b17218
	v_ldexp_f32 v15, v15, v17
	v_cndmask_b32_e32 v15, 0, v15, vcc
	v_cmp_ngt_f32_e32 vcc, s0, v13
	s_nop 1
	v_cndmask_b32_e32 v13, v230, v15, vcc
	v_sub_f32_e32 v13, 1.0, v13
